# plain (W_o/down) GEMM: the two wave halves' epilogues un-aligned (no extra barriers around the epilogue; one for the leading half at phase exit)
# baseline (speedup 1.0000x reference)
; __device__ __forceinline__ u32x4 pack8(const f32x4 a, const f32x4 b) { u32x4 w; w.x = cvt_pk_bf16(a[0], a[1]); w.y = cvt_pk_bf16(a[2], a[3]); w.z = cvt_pk_bf16(b[0], b[1]); w.w = cvt_pk_bf16(b[2], b[3]); return w; }
; #define PG8_WAIT_V(n) asm volatile("s_waitcnt vmcnt(" #n ")" ::: "memory")
; #define PG8_BAR __builtin_amdgcn_s_barrier()
;     __device__ __forceinline__ void operator()(const f32x4 (&acc)[2][2][4][2], const Unit& u, int wr, int wc, int fr, int fq) const {
;         const int row0 = u.pm * BM + wr * 64 + fr, col0 = u.pn * BM + wc * 32 + 8 * fq;
; #pragma unroll
;         for (int ai = 0; ai < 2; ++ai)
; #pragma unroll
;             for (int m = 0; m < 4; ++m) { bf16_t* rowp = O + (size_t)(row0 + ai * HALF + m * 16) * ldc + col0;
; #pragma unroll
;                 for (int bj = 0; bj < 2; ++bj) *(u32x4*)(rowp + bj * HALF) = pack8(acc[ai][bj][m][0], acc[ai][bj][m][1]); }
;     }
; template <class Epi, class Sched, bool ALIGN_EPI = false, bool SP2 = false>
; __device__ __forceinline__ void gemm_phase(PG8_LAS unsigned char* lds, const Gemm g, const Sched& S, const Epi& E) {
;     ...
;         if constexpr (ALIGN_EPI) { if (wr == 0) PG8_BAR; }
;         if constexpr (!Epi::AFTER_DRAIN) { E(acc, cur, wr, wc, fr, fq); S.done(cur); }
;         if (!has_next) break;
; #pragma unroll
;         for (int a = 0; a < 2; ++a)
; #pragma unroll
;             for (int b = 0; b < 2; ++b)
; #pragma unroll
;                 for (int m = 0; m < 4; ++m)
; #pragma unroll
;                     for (int n = 0; n < 2; ++n) acc[a][b][m][n] = (f32x4){0.f, 0.f, 0.f, 0.f};
;         cur = nxt; cA = nA; cB = nB; ++ui;
;         if constexpr (ALIGN_EPI) { if (wr == 1) PG8_BAR; }
;     }
;     PG8_WAIT_V(0);
;     if constexpr (!ALIGN_EPI) { if (wr == 0) PG8_BAR; }
.LBB0_256:
	v_lshl_add_u32 v148, s81, 8, v1
	v_lshl_or_b32 v144, s80, 8, v146
	v_ashrrev_i32_e32 v149, 31, v148
	v_ashrrev_i32_e32 v145, 31, v144
	v_lshlrev_b64 v[150:151], 11, v[148:149]
	v_lshl_add_u64 v[150:151], s[48:49], 0, v[150:151]
	v_lshlrev_b64 v[152:153], 1, v[144:145]
	v_lshl_add_u64 v[144:145], v[150:151], 0, v[152:153]
	v_cvt_pk_bf16_f32 v130, v130, v131
	v_cvt_pk_bf16_f32 v131, v132, v133
	v_cvt_pk_bf16_f32 v132, v126, v127
	v_cvt_pk_bf16_f32 v133, v128, v129
	global_store_dwordx4 v[144:145], v[130:133], off
	v_cvt_pk_bf16_f32 v118, v118, v119
	v_cvt_pk_bf16_f32 v119, v120, v121
	v_cvt_pk_bf16_f32 v120, v110, v111
	v_or_b32_e32 v110, 16, v148
	v_ashrrev_i32_e32 v111, 31, v110
	v_lshlrev_b64 v[110:111], 11, v[110:111]
	v_lshl_add_u64 v[110:111], s[48:49], 0, v[110:111]
	v_cvt_pk_bf16_f32 v121, v112, v113
	global_store_dwordx4 v[144:145], v[118:121], off offset:256
	s_mov_b32 s8, 0x40000
	s_nop 0
	v_lshl_add_u64 v[118:119], v[110:111], 0, v[152:153]
	v_cvt_pk_bf16_f32 v110, v122, v123
	v_cvt_pk_bf16_f32 v111, v124, v125
	v_cvt_pk_bf16_f32 v112, v114, v115
	v_cvt_pk_bf16_f32 v113, v116, v117
	global_store_dwordx4 v[118:119], v[110:113], off
	v_cvt_pk_bf16_f32 v102, v102, v103
	v_cvt_pk_bf16_f32 v103, v104, v105
	v_cvt_pk_bf16_f32 v104, v94, v95
	v_or_b32_e32 v94, 32, v148
	v_ashrrev_i32_e32 v95, 31, v94
	v_lshlrev_b64 v[94:95], 11, v[94:95]
	v_lshl_add_u64 v[94:95], s[48:49], 0, v[94:95]
	v_cvt_pk_bf16_f32 v105, v96, v97
	global_store_dwordx4 v[118:119], v[102:105], off offset:256
	s_nop 1
	v_lshl_add_u64 v[102:103], v[94:95], 0, v[152:153]
	v_cvt_pk_bf16_f32 v94, v106, v107
	v_cvt_pk_bf16_f32 v95, v108, v109
	v_cvt_pk_bf16_f32 v96, v98, v99
	v_cvt_pk_bf16_f32 v97, v100, v101
	global_store_dwordx4 v[102:103], v[94:97], off
	v_cvt_pk_bf16_f32 v86, v86, v87
	v_cvt_pk_bf16_f32 v87, v88, v89
	v_cvt_pk_bf16_f32 v88, v78, v79
	v_or_b32_e32 v78, 48, v148
	v_ashrrev_i32_e32 v79, 31, v78
	v_lshlrev_b64 v[78:79], 11, v[78:79]
	v_lshl_add_u64 v[78:79], s[48:49], 0, v[78:79]
	v_cvt_pk_bf16_f32 v89, v80, v81
	global_store_dwordx4 v[102:103], v[86:89], off offset:256
	s_nop 1
	v_lshl_add_u64 v[86:87], v[78:79], 0, v[152:153]
	v_cvt_pk_bf16_f32 v78, v90, v91
	v_cvt_pk_bf16_f32 v79, v92, v93
	v_cvt_pk_bf16_f32 v80, v82, v83
	v_cvt_pk_bf16_f32 v81, v84, v85
	global_store_dwordx4 v[86:87], v[78:81], off
	v_cvt_pk_bf16_f32 v74, v74, v75
	v_cvt_pk_bf16_f32 v75, v76, v77
	v_cvt_pk_bf16_f32 v76, v70, v71
	v_cvt_pk_bf16_f32 v77, v72, v73
	global_store_dwordx4 v[86:87], v[74:77], off offset:256
	v_cvt_pk_bf16_f32 v66, v66, v67
	v_cvt_pk_bf16_f32 v67, v68, v69
	v_cvt_pk_bf16_f32 v68, v62, v63
	v_add_co_u32_e32 v62, vcc, s8, v144
	v_lshl_add_u64 v[70:71], v[144:145], 0, s[86:87]
	s_nop 0
	v_addc_co_u32_e32 v63, vcc, 0, v145, vcc
	v_cvt_pk_bf16_f32 v69, v64, v65
	global_store_dwordx4 v[62:63], v[66:69], off
	v_cvt_pk_bf16_f32 v54, v54, v55
	v_cvt_pk_bf16_f32 v55, v56, v57
	s_mov_b64 s[8:9], 0x48000
	v_cvt_pk_bf16_f32 v56, v46, v47
	v_cvt_pk_bf16_f32 v57, v48, v49
	global_store_dwordx4 v[70:71], v[54:57], off offset:256
	v_cvt_pk_bf16_f32 v46, v58, v59
	v_cvt_pk_bf16_f32 v47, v60, v61
	v_cvt_pk_bf16_f32 v48, v50, v51
	v_cvt_pk_bf16_f32 v49, v52, v53
	s_nop 1
	v_lshl_add_u64 v[54:55], v[144:145], 0, s[8:9]
	s_mov_b32 s8, 0x48000
	v_add_co_u32_e32 v50, vcc, s8, v144
	s_mov_b64 s[8:9], 0x50000
	s_nop 0
	v_addc_co_u32_e32 v51, vcc, 0, v145, vcc
	global_store_dwordx4 v[50:51], v[46:49], off
	v_cvt_pk_bf16_f32 v38, v38, v39
	v_cvt_pk_bf16_f32 v39, v40, v41
	v_cvt_pk_bf16_f32 v40, v30, v31
	v_cvt_pk_bf16_f32 v41, v32, v33
	global_store_dwordx4 v[54:55], v[38:41], off offset:256
	v_cvt_pk_bf16_f32 v30, v42, v43
	v_cvt_pk_bf16_f32 v31, v44, v45
	v_cvt_pk_bf16_f32 v32, v34, v35
	v_cvt_pk_bf16_f32 v33, v36, v37
	s_nop 1
	v_lshl_add_u64 v[38:39], v[144:145], 0, s[8:9]
	s_mov_b32 s8, 0x50000
	v_add_co_u32_e32 v34, vcc, s8, v144
	s_mov_b64 s[8:9], 0x58000
	s_nop 0
	v_addc_co_u32_e32 v35, vcc, 0, v145, vcc
	global_store_dwordx4 v[34:35], v[30:33], off
	v_cvt_pk_bf16_f32 v22, v22, v23
	v_cvt_pk_bf16_f32 v23, v24, v25
	v_cvt_pk_bf16_f32 v24, v10, v11
	v_cvt_pk_bf16_f32 v25, v12, v13
	global_store_dwordx4 v[38:39], v[22:25], off offset:256
	v_cvt_pk_bf16_f32 v10, v26, v27
	v_cvt_pk_bf16_f32 v11, v28, v29
	v_cvt_pk_bf16_f32 v12, v18, v19
	v_cvt_pk_bf16_f32 v13, v20, v21
	s_nop 1
	v_lshl_add_u64 v[22:23], v[144:145], 0, s[8:9]
	s_mov_b32 s8, 0x58000
	v_add_co_u32_e32 v18, vcc, s8, v144
	s_nop 1
	v_addc_co_u32_e32 v19, vcc, 0, v145, vcc
	s_and_b64 vcc, exec, s[0:1]
	s_mov_b64 s[0:1], -1
	global_store_dwordx4 v[18:19], v[10:13], off
	v_cvt_pk_bf16_f32 v6, v6, v7
	v_cvt_pk_bf16_f32 v7, v8, v9
	v_cvt_pk_bf16_f32 v8, v2, v3
	v_cvt_pk_bf16_f32 v9, v4, v5
	global_store_dwordx4 v[22:23], v[6:9], off offset:256
	s_cbranch_vccnz .LBB0_245
	s_andn2_b64 vcc, exec, s[28:29]
	s_cbranch_vccnz .LBB0_244
	s_branch .LBB0_244
.LBB0_259:
	s_and_b64 vcc, exec, s[82:83]
	s_cbranch_vccz .Lua_skip
	s_barrier
